# ret_sample_pair: gate and state loads issued right behind the q/k/v loads instead of after the barrier
# speedup vs baseline: 1.0315x; 1.0021x over previous
.LBB0_444:
	s_cmpk_gt_i32 s30, 0xff
	s_mov_b64 s[0:1], -1
	s_cbranch_scc0 .LBB0_463
	s_cmpk_gt_u32 s30, 0x17f
	s_cbranch_scc0 .LBB0_457
	s_cmpk_gt_u32 s30, 0x27f
	s_cbranch_scc0 .LBB0_454
	v_mov_b32_e32 v6, v226
	s_lshl_b32 s0, s30, 1
	v_readfirstlane_b32 s21, v6
	s_ashr_i32 s22, s21, 8
	s_add_i32 s0, s0, s22
	s_add_i32 s20, s0, 0xfffffb00
	s_and_b32 s40, s20, 3
	v_cvt_f32_ubyte0_e32 v0, s40
	v_sub_f32_e32 v0, 0xc0a00000, v0
	v_cmp_gt_f32_e32 vcc, s3, v0
	s_and_b64 s[0:1], vcc, exec
	s_cselect_b32 s0, 0xffffffc0, 0
	v_cndmask_b32_e32 v1, 0, v233, vcc
	v_add_f32_e32 v0, v0, v1
	v_exp_f32_e32 v0, v0
	v_and_b32_e32 v7, 0xff, v6
	s_bfe_u32 s23, s21, 0x20006
	v_and_b32_e32 v125, 63, v6
	v_ldexp_f32 v0, v0, s0
	s_lshl_b32 s0, s22, 15
	s_add_i32 s31, s0, 0
	s_and_b32 s0, s20, -4
	v_sub_f32_e32 v8, 1.0, v0
	s_addk_i32 s0, 0x4000
	v_and_b32_e32 v0, 0x7f, v6
	s_lshl_b32 s22, s40, 7
	s_ashr_i32 s1, s0, 31
	v_or_b32_e32 v4, s22, v0
	v_bfe_u32 v0, v6, 7, 1
	v_or_b32_e32 v0, s0, v0
	v_mov_b32_e32 v1, s1
	v_lshlrev_b64 v[2:3], 10, v[0:1]
	v_or_b32_e32 v0, 0x100, v7
	v_lshlrev_b32_e32 v9, 1, v4
	v_lshrrev_b32_e32 v0, 7, v0
	v_or_b32_e32 v2, v2, v9
	v_or_b32_e32 v0, s0, v0
	v_lshl_add_u64 v[4:5], s[38:39], 0, v[2:3]
	v_lshlrev_b64 v[0:1], 10, v[0:1]
	global_load_ushort v10, v[4:5], off
	v_lshl_add_u64 v[4:5], s[50:51], 0, v[2:3]
	v_lshl_add_u64 v[2:3], s[90:91], 0, v[2:3]
	v_or_b32_e32 v0, v0, v9
	global_load_ushort v4, v[4:5], off
	v_log_f32_e32 v124, v8
	global_load_ushort v5, v[2:3], off
	v_lshl_add_u64 v[2:3], s[38:39], 0, v[0:1]
	global_load_ushort v9, v[2:3], off
	v_lshl_add_u64 v[2:3], s[50:51], 0, v[0:1]
	v_lshl_add_u64 v[0:1], s[90:91], 0, v[0:1]
	global_load_ushort v11, v[2:3], off
	global_load_ushort v12, v[0:1], off
	s_or_b32 s98, s0, s23
	s_mov_b32 s99, s1
	s_lshl_b64 s[98:99], s[98:99], 10
	s_add_u32 s98, s54, s98
	s_addc_u32 s99, s55, s99
	s_lshl_b32 s100, s40, 8
	s_add_u32 s98, s98, s100
	s_addc_u32 s99, s99, 0
	v_lshlrev_b32_e32 v99, 1, v125
	global_load_ushort v122, v99, s[98:99]
	global_load_ushort v123, v99, s[98:99] offset:128
	s_ashr_i32 s101, s20, 31
	s_mov_b32 s100, s20
	s_lshl_b64 s[100:101], s[100:101], 16
	s_add_u32 s100, s24, s100
	s_addc_u32 s101, s25, s101
	v_lshlrev_b32_e32 v200, 4, v6
	v_bfe_u32 v201, v6, 5, 3
	v_and_b32_e32 v200, 0x1f0, v200
	v_lshl_or_b32 v200, v201, 13, v200
	global_load_dwordx4 v[76:79], v200, s[100:101] nt
	global_load_dwordx4 v[72:75], v200, s[100:101] offset:512 nt
	global_load_dwordx4 v[68:71], v200, s[100:101] offset:1024 nt
	global_load_dwordx4 v[64:67], v200, s[100:101] offset:1536 nt
	global_load_dwordx4 v[60:63], v200, s[100:101] offset:2048 nt
	global_load_dwordx4 v[56:59], v200, s[100:101] offset:2560 nt
	global_load_dwordx4 v[52:55], v200, s[100:101] offset:3072 nt
	global_load_dwordx4 v[48:51], v200, s[100:101] offset:3584 nt
	s_add_u32 s100, s100, 0x1000
	s_addc_u32 s101, s101, 0
	global_load_dwordx4 v[44:47], v200, s[100:101] nt
	global_load_dwordx4 v[40:43], v200, s[100:101] offset:512 nt
	global_load_dwordx4 v[36:39], v200, s[100:101] offset:1024 nt
	global_load_dwordx4 v[32:35], v200, s[100:101] offset:1536 nt
	global_load_dwordx4 v[28:31], v200, s[100:101] offset:2048 nt
	global_load_dwordx4 v[24:27], v200, s[100:101] offset:2560 nt
	global_load_dwordx4 v[20:23], v200, s[100:101] offset:3072 nt
	global_load_dwordx4 v[16:19], v200, s[100:101] offset:3584 nt
	s_waitcnt vmcnt(18)
	v_lshl_add_u32 v1, v7, 2, s31
	v_lshlrev_b32_e32 v0, 16, v10
	v_lshlrev_b32_e32 v2, 16, v4
	v_lshlrev_b32_e32 v4, 16, v9
	ds_write2st64_b32 v1, v0, v4 offset1:4
	v_lshlrev_b32_e32 v0, 16, v11
	v_lshlrev_b32_e32 v3, 16, v5
	ds_write2st64_b32 v1, v2, v0 offset0:8 offset1:12
	v_lshlrev_b32_e32 v0, 16, v12
	ds_write2st64_b32 v1, v3, v0 offset0:16 offset1:20
	s_or_b32 s0, s0, s23
	v_add_f32_e32 v0, v124, v124
	s_lshl_b64 s[34:35], s[0:1], 10
	v_cmp_gt_f32_e32 vcc, s3, v0
	s_add_u32 s21, s54, s34
	s_addc_u32 s35, s55, s35
	v_cndmask_b32_e32 v0, 0, v233, vcc
	s_lshl_b32 s34, s40, 8
	v_fmac_f32_e32 v0, 2.0, v124
	s_add_u32 s34, s21, s34
	v_exp_f32_e32 v0, v0
	s_addc_u32 s35, s35, 0
	v_lshlrev_b32_e32 v99, 1, v125
	s_and_b64 s[34:35], vcc, exec
	s_cselect_b32 s21, 0xffffffc0, 0
	v_ldexp_f32 v128, v0, s21
	s_ashr_i32 s21, s20, 31
	s_lshl_b64 s[20:21], s[20:21], 16
	s_add_u32 s34, s24, s20
	v_lshlrev_b32_e32 v0, 4, v6
	v_bfe_u32 v126, v6, 5, 3
	s_addc_u32 s35, s25, s21
	v_and_b32_e32 v208, 0x1f0, v0
	v_lshlrev_b32_e32 v96, 13, v126
	v_mov_b32_e32 v97, v209
	v_add_u32_e32 v127, s31, v208
	s_waitcnt lgkmcnt(0)
	s_barrier
	ds_read_b128 v[12:15], v127 offset:4096
	ds_read_b128 v[8:11], v127 offset:4608
	ds_read_b128 v[4:7], v127 offset:5120
	ds_read_b128 v[0:3], v127 offset:5632
	s_movk_i32 s34, 0x1000
	v_mul_f32_e32 v80, 4.0, v124
	s_nop 0
	v_cmp_gt_f32_e32 vcc, s3, v80
	v_mul_f32_e32 v81, 0x40400000, v124
	s_and_b64 s[34:35], vcc, exec
	v_cndmask_b32_e32 v80, 0, v233, vcc
	v_fmac_f32_e32 v80, 4.0, v124
	v_exp_f32_e32 v80, v80
	s_cselect_b32 s34, 0xffffffc0, 0
	v_cmp_gt_f32_e32 vcc, s3, v81
	v_lshl_add_u32 v131, v126, 6, s31
	v_ldexp_f32 v98, v80, s34
	v_cndmask_b32_e32 v80, 0, v233, vcc
	v_fmac_f32_e32 v80, 0x40400000, v124
	v_exp_f32_e32 v80, v80
	s_and_b64 s[34:35], vcc, exec
	s_cselect_b32 s34, 0xffffffc0, 0
	v_cmp_gt_f32_e32 vcc, s3, v124
	v_ldexp_f32 v130, v80, s34
	s_nop 0
	v_cndmask_b32_e32 v80, 0, v233, vcc
	v_add_f32_e32 v80, v124, v80
	v_exp_f32_e32 v80, v80
	s_and_b64 s[34:35], vcc, exec
	ds_read_b128 v[102:105], v131 offset:2048
	ds_read_b128 v[110:113], v131 offset:3072
	s_cselect_b32 s34, 0xffffffc0, 0
	v_ldexp_f32 v129, v80, s34
	ds_read_b128 v[80:83], v131
	ds_read_b128 v[84:87], v131 offset:512
	ds_read_b128 v[88:91], v131 offset:1024
	ds_read_b128 v[92:95], v131 offset:1536
	s_waitcnt lgkmcnt(5)
	v_mul_f32_e32 v102, v130, v102
	v_pk_mul_f32 v[106:107], v[12:13], v[102:103] op_sel_hi:[1,0]
	v_pk_mul_f32 v[108:109], v[14:15], v[102:103] op_sel_hi:[1,0]
	ds_read_b128 v[114:117], v131 offset:3584
	s_add_u32 s20, s26, s20
	s_addc_u32 s21, s27, s21
	v_lshl_add_u64 v[100:101], s[20:21], 0, v[208:209]
	v_lshl_add_u64 v[144:145], v[100:101], 0, v[96:97]
	v_or_b32_e32 v208, 0x200, v96
	s_add_i32 s20, s23, 1
	s_lshl_b32 s34, s23, 9
	s_waitcnt vmcnt(15) lgkmcnt(4)
	v_pk_fma_f32 v[118:119], v[78:79], v[80:81], 0 op_sel_hi:[1,0,0]
	v_pk_fma_f32 v[120:121], v[76:77], v[80:81], 0 op_sel_hi:[1,0,0]
	s_waitcnt lgkmcnt(3)
	v_pk_fma_f32 v[132:133], v[78:79], v[84:85], 0 op_sel_hi:[1,0,0]
	v_pk_fma_f32 v[134:135], v[76:77], v[84:85], 0 op_sel_hi:[1,0,0]
	s_waitcnt lgkmcnt(2)
	v_pk_fma_f32 v[136:137], v[78:79], v[88:89], 0 op_sel_hi:[1,0,0]
	v_pk_fma_f32 v[138:139], v[76:77], v[88:89], 0 op_sel_hi:[1,0,0]
	s_waitcnt lgkmcnt(1)
	v_pk_fma_f32 v[140:141], v[78:79], v[92:93], 0 op_sel_hi:[1,0,0]
	v_pk_fma_f32 v[142:143], v[76:77], v[92:93], 0 op_sel_hi:[1,0,0]
	v_pk_fma_f32 v[78:79], v[98:99], v[78:79], v[108:109] op_sel_hi:[0,1,1]
	v_pk_fma_f32 v[76:77], v[98:99], v[76:77], v[106:107] op_sel_hi:[0,1,1]
	ds_read_b128 v[106:109], v131 offset:2560
	s_waitcnt lgkmcnt(0)
	v_mul_f32_e32 v102, v128, v106
	v_pk_fma_f32 v[78:79], v[10:11], v[102:103], v[78:79] op_sel_hi:[1,0,1]
	v_pk_fma_f32 v[76:77], v[8:9], v[102:103], v[76:77] op_sel_hi:[1,0,1]
	v_mul_f32_e32 v102, v129, v110
	v_pk_fma_f32 v[78:79], v[6:7], v[102:103], v[78:79] op_sel_hi:[1,0,1]
	v_pk_fma_f32 v[76:77], v[4:5], v[102:103], v[76:77] op_sel_hi:[1,0,1]
	v_pk_fma_f32 v[78:79], v[2:3], v[114:115], v[78:79] op_sel_hi:[1,0,1]
	v_pk_fma_f32 v[76:77], v[0:1], v[114:115], v[76:77] op_sel_hi:[1,0,1]
	v_mul_f32_e32 v102, v130, v103
	global_store_dwordx4 v[144:145], v[76:79], off nt
	s_waitcnt vmcnt(15)
	s_nop 0
	v_pk_fma_f32 v[76:77], v[74:75], v[80:81], v[118:119] op_sel:[0,1,0]
	v_pk_fma_f32 v[78:79], v[72:73], v[80:81], v[120:121] op_sel:[0,1,0]
	v_pk_fma_f32 v[80:81], v[74:75], v[84:85], v[132:133] op_sel:[0,1,0]
	v_pk_mul_f32 v[132:133], v[12:13], v[102:103] op_sel_hi:[1,0]
	v_pk_mul_f32 v[102:103], v[14:15], v[102:103] op_sel_hi:[1,0]
	v_pk_fma_f32 v[84:85], v[72:73], v[84:85], v[134:135] op_sel:[0,1,0]
	v_pk_fma_f32 v[118:119], v[74:75], v[88:89], v[136:137] op_sel:[0,1,0]
	v_pk_fma_f32 v[88:89], v[72:73], v[88:89], v[138:139] op_sel:[0,1,0]
	v_pk_fma_f32 v[120:121], v[74:75], v[92:93], v[140:141] op_sel:[0,1,0]
	v_pk_fma_f32 v[92:93], v[72:73], v[92:93], v[142:143] op_sel:[0,1,0]
	v_pk_fma_f32 v[74:75], v[98:99], v[74:75], v[102:103] op_sel_hi:[0,1,1]
	v_pk_fma_f32 v[72:73], v[98:99], v[72:73], v[132:133] op_sel_hi:[0,1,1]
	v_mul_f32_e32 v102, v128, v107
	v_pk_fma_f32 v[74:75], v[10:11], v[102:103], v[74:75] op_sel_hi:[1,0,1]
	v_pk_fma_f32 v[72:73], v[8:9], v[102:103], v[72:73] op_sel_hi:[1,0,1]
	v_mul_f32_e32 v102, v129, v111
	v_pk_fma_f32 v[74:75], v[6:7], v[102:103], v[74:75] op_sel_hi:[1,0,1]
	v_pk_fma_f32 v[72:73], v[4:5], v[102:103], v[72:73] op_sel_hi:[1,0,1]
	v_pk_fma_f32 v[74:75], v[2:3], v[114:115], v[74:75] op_sel:[0,1,0]
	v_pk_fma_f32 v[72:73], v[0:1], v[114:115], v[72:73] op_sel:[0,1,0]
	v_lshl_add_u64 v[102:103], v[100:101], 0, v[208:209]
	global_store_dwordx4 v[102:103], v[72:75], off nt
	s_waitcnt vmcnt(15)
	v_pk_fma_f32 v[92:93], v[68:69], v[94:95], v[92:93] op_sel_hi:[1,0,1]
	v_or_b32_e32 v208, 0x400, v96
	v_pk_fma_f32 v[72:73], v[70:71], v[82:83], v[76:77] op_sel_hi:[1,0,1]
	v_pk_fma_f32 v[74:75], v[68:69], v[82:83], v[78:79] op_sel_hi:[1,0,1]
	v_mul_f32_e32 v82, v130, v104
	v_pk_mul_f32 v[102:103], v[12:13], v[82:83] op_sel_hi:[1,0]
	v_pk_mul_f32 v[106:107], v[14:15], v[82:83] op_sel_hi:[1,0]
	v_pk_fma_f32 v[76:77], v[70:71], v[86:87], v[80:81] op_sel_hi:[1,0,1]
	v_pk_fma_f32 v[78:79], v[68:69], v[86:87], v[84:85] op_sel_hi:[1,0,1]
	v_pk_fma_f32 v[80:81], v[70:71], v[90:91], v[118:119] op_sel_hi:[1,0,1]
	v_pk_fma_f32 v[84:85], v[68:69], v[90:91], v[88:89] op_sel_hi:[1,0,1]
	v_pk_fma_f32 v[88:89], v[70:71], v[94:95], v[120:121] op_sel_hi:[1,0,1]
	v_pk_fma_f32 v[70:71], v[98:99], v[70:71], v[106:107] op_sel_hi:[0,1,1]
	v_pk_fma_f32 v[68:69], v[98:99], v[68:69], v[102:103] op_sel_hi:[0,1,1]
	v_mul_f32_e32 v82, v128, v108
	v_pk_fma_f32 v[70:71], v[10:11], v[82:83], v[70:71] op_sel_hi:[1,0,1]
	v_pk_fma_f32 v[68:69], v[8:9], v[82:83], v[68:69] op_sel_hi:[1,0,1]
	v_mul_f32_e32 v82, v129, v112
	v_pk_fma_f32 v[70:71], v[6:7], v[82:83], v[70:71] op_sel_hi:[1,0,1]
	v_pk_fma_f32 v[68:69], v[4:5], v[82:83], v[68:69] op_sel_hi:[1,0,1]
	v_pk_fma_f32 v[70:71], v[2:3], v[116:117], v[70:71] op_sel_hi:[1,0,1]
	v_pk_fma_f32 v[68:69], v[0:1], v[116:117], v[68:69] op_sel_hi:[1,0,1]
	v_lshl_add_u64 v[102:103], v[100:101], 0, v[208:209]
	global_store_dwordx4 v[102:103], v[68:71], off nt
	v_or_b32_e32 v208, 0x600, v96
	s_nop 0
	v_mov_b32_e32 v68, v83
	s_waitcnt vmcnt(15)
	v_pk_fma_f32 v[72:73], v[66:67], v[68:69], v[72:73] op_sel_hi:[1,0,1]
	v_pk_fma_f32 v[74:75], v[64:65], v[68:69], v[74:75] op_sel_hi:[1,0,1]
	v_mov_b32_e32 v68, v87
	v_pk_fma_f32 v[76:77], v[66:67], v[68:69], v[76:77] op_sel_hi:[1,0,1]
	v_pk_fma_f32 v[78:79], v[64:65], v[68:69], v[78:79] op_sel_hi:[1,0,1]
	v_mov_b32_e32 v68, v91
	v_pk_fma_f32 v[80:81], v[66:67], v[68:69], v[80:81] op_sel_hi:[1,0,1]
	v_pk_fma_f32 v[82:83], v[64:65], v[68:69], v[84:85] op_sel_hi:[1,0,1]
	v_mov_b32_e32 v68, v95
	v_pk_fma_f32 v[84:85], v[66:67], v[68:69], v[88:89] op_sel_hi:[1,0,1]
	v_pk_fma_f32 v[86:87], v[64:65], v[68:69], v[92:93] op_sel_hi:[1,0,1]
	v_mul_f32_e32 v68, v130, v105
	v_pk_mul_f32 v[70:71], v[12:13], v[68:69] op_sel_hi:[1,0]
	v_pk_mul_f32 v[68:69], v[14:15], v[68:69] op_sel_hi:[1,0]
	v_pk_fma_f32 v[64:65], v[98:99], v[64:65], v[70:71] op_sel_hi:[0,1,1]
	v_pk_fma_f32 v[66:67], v[98:99], v[66:67], v[68:69] op_sel_hi:[0,1,1]
	v_mul_f32_e32 v68, v128, v109
	v_pk_fma_f32 v[66:67], v[10:11], v[68:69], v[66:67] op_sel_hi:[1,0,1]
	v_pk_fma_f32 v[64:65], v[8:9], v[68:69], v[64:65] op_sel_hi:[1,0,1]
	v_mul_f32_e32 v68, v129, v113
	v_pk_fma_f32 v[66:67], v[6:7], v[68:69], v[66:67] op_sel_hi:[1,0,1]
	v_pk_fma_f32 v[64:65], v[4:5], v[68:69], v[64:65] op_sel_hi:[1,0,1]
	v_mov_b32_e32 v68, v117
	v_pk_fma_f32 v[66:67], v[2:3], v[68:69], v[66:67] op_sel_hi:[1,0,1]
	v_pk_fma_f32 v[64:65], v[0:1], v[68:69], v[64:65] op_sel_hi:[1,0,1]
	v_lshl_add_u64 v[68:69], v[100:101], 0, v[208:209]
	global_store_dwordx4 v[68:69], v[64:67], off nt
	ds_read_b128 v[68:71], v131 offset:16
	ds_read_b128 v[64:67], v131 offset:32
	v_or_b32_e32 v208, 0x800, v96
	s_waitcnt vmcnt(15) lgkmcnt(1)
	v_pk_fma_f32 v[102:103], v[62:63], v[68:69], v[72:73] op_sel_hi:[1,0,1]
	v_pk_fma_f32 v[104:105], v[60:61], v[68:69], v[74:75] op_sel_hi:[1,0,1]
	ds_read_b128 v[72:75], v131 offset:528
	s_waitcnt vmcnt(14)
	v_pk_fma_f32 v[102:103], v[58:59], v[68:69], v[102:103] op_sel:[0,1,0]
	v_pk_fma_f32 v[68:69], v[56:57], v[68:69], v[104:105] op_sel:[0,1,0]
	s_waitcnt lgkmcnt(0)
	v_pk_fma_f32 v[106:107], v[62:63], v[72:73], v[76:77] op_sel_hi:[1,0,1]
	v_pk_fma_f32 v[108:109], v[60:61], v[72:73], v[78:79] op_sel_hi:[1,0,1]
	ds_read_b128 v[76:79], v131 offset:1040
	v_pk_fma_f32 v[104:105], v[58:59], v[72:73], v[106:107] op_sel:[0,1,0]
	v_pk_fma_f32 v[72:73], v[56:57], v[72:73], v[108:109] op_sel:[0,1,0]
	s_waitcnt lgkmcnt(0)
	v_pk_fma_f32 v[110:111], v[62:63], v[76:77], v[80:81] op_sel_hi:[1,0,1]
	v_pk_fma_f32 v[112:113], v[60:61], v[76:77], v[82:83] op_sel_hi:[1,0,1]
	ds_read_b128 v[80:83], v131 offset:1552
	v_pk_fma_f32 v[106:107], v[58:59], v[76:77], v[110:111] op_sel:[0,1,0]
	v_pk_fma_f32 v[76:77], v[56:57], v[76:77], v[112:113] op_sel:[0,1,0]
	s_waitcnt lgkmcnt(0)
	v_pk_fma_f32 v[114:115], v[62:63], v[80:81], v[84:85] op_sel_hi:[1,0,1]
	v_pk_fma_f32 v[116:117], v[60:61], v[80:81], v[86:87] op_sel_hi:[1,0,1]
	ds_read_b128 v[84:87], v131 offset:2064
	v_pk_fma_f32 v[108:109], v[58:59], v[80:81], v[114:115] op_sel:[0,1,0]
	v_pk_fma_f32 v[80:81], v[56:57], v[80:81], v[116:117] op_sel:[0,1,0]
	s_waitcnt vmcnt(13)
	v_pk_fma_f32 v[76:77], v[52:53], v[78:79], v[76:77] op_sel_hi:[1,0,1]
	v_pk_fma_f32 v[80:81], v[52:53], v[82:83], v[80:81] op_sel_hi:[1,0,1]
	s_waitcnt lgkmcnt(0)
	v_mul_f32_e32 v84, v130, v84
	v_pk_mul_f32 v[88:89], v[12:13], v[84:85] op_sel_hi:[1,0]
	v_pk_mul_f32 v[90:91], v[14:15], v[84:85] op_sel_hi:[1,0]
	v_pk_fma_f32 v[88:89], v[98:99], v[60:61], v[88:89] op_sel_hi:[0,1,1]
	v_pk_fma_f32 v[90:91], v[98:99], v[62:63], v[90:91] op_sel_hi:[0,1,1]
	ds_read_b128 v[60:63], v131 offset:2576
	s_waitcnt lgkmcnt(0)
	v_mul_f32_e32 v60, v128, v60
	v_pk_fma_f32 v[92:93], v[10:11], v[60:61], v[90:91] op_sel_hi:[1,0,1]
	v_pk_fma_f32 v[94:95], v[8:9], v[60:61], v[88:89] op_sel_hi:[1,0,1]
	ds_read_b128 v[88:91], v131 offset:3088
	v_mul_f32_e32 v62, v128, v62
	s_waitcnt lgkmcnt(0)
	v_mul_f32_e32 v60, v129, v88
	v_pk_fma_f32 v[118:119], v[6:7], v[60:61], v[92:93] op_sel_hi:[1,0,1]
	v_pk_fma_f32 v[120:121], v[4:5], v[60:61], v[94:95] op_sel_hi:[1,0,1]
	ds_read_b128 v[92:95], v131 offset:3600
	v_mul_f32_e32 v60, v130, v85
	v_pk_mul_f32 v[84:85], v[12:13], v[60:61] op_sel_hi:[1,0]
	v_pk_mul_f32 v[110:111], v[14:15], v[60:61] op_sel_hi:[1,0]
	v_pk_fma_f32 v[56:57], v[98:99], v[56:57], v[84:85] op_sel_hi:[0,1,1]
	v_pk_fma_f32 v[58:59], v[98:99], v[58:59], v[110:111] op_sel_hi:[0,1,1]
	v_mul_f32_e32 v60, v128, v61
	v_pk_fma_f32 v[58:59], v[10:11], v[60:61], v[58:59] op_sel_hi:[1,0,1]
	v_pk_fma_f32 v[56:57], v[8:9], v[60:61], v[56:57] op_sel_hi:[1,0,1]
	v_mul_f32_e32 v60, v129, v89
	s_waitcnt lgkmcnt(0)
	v_pk_fma_f32 v[134:135], v[2:3], v[92:93], v[118:119] op_sel_hi:[1,0,1]
	v_lshl_add_u64 v[118:119], v[100:101], 0, v[208:209]
	v_pk_fma_f32 v[58:59], v[6:7], v[60:61], v[58:59] op_sel_hi:[1,0,1]
	v_pk_fma_f32 v[56:57], v[4:5], v[60:61], v[56:57] op_sel_hi:[1,0,1]
	v_or_b32_e32 v208, 0xa00, v96
	v_pk_fma_f32 v[58:59], v[2:3], v[92:93], v[58:59] op_sel:[0,1,0]
	v_pk_fma_f32 v[56:57], v[0:1], v[92:93], v[56:57] op_sel:[0,1,0]
	v_lshl_add_u64 v[60:61], v[100:101], 0, v[208:209]
	global_store_dwordx4 v[60:61], v[56:59], off nt
	v_pk_fma_f32 v[132:133], v[0:1], v[92:93], v[120:121] op_sel_hi:[1,0,1]
	v_pk_fma_f32 v[60:61], v[54:55], v[74:75], v[104:105] op_sel_hi:[1,0,1]
	v_pk_fma_f32 v[56:57], v[54:55], v[70:71], v[102:103] op_sel_hi:[1,0,1]
	v_pk_fma_f32 v[58:59], v[52:53], v[70:71], v[68:69] op_sel_hi:[1,0,1]
	v_mul_f32_e32 v70, v130, v86
	v_pk_mul_f32 v[88:89], v[12:13], v[70:71] op_sel_hi:[1,0]
	v_pk_mul_f32 v[92:93], v[14:15], v[70:71] op_sel_hi:[1,0]
	v_pk_fma_f32 v[68:69], v[52:53], v[74:75], v[72:73] op_sel_hi:[1,0,1]
	v_pk_fma_f32 v[72:73], v[54:55], v[78:79], v[106:107] op_sel_hi:[1,0,1]
	v_pk_fma_f32 v[84:85], v[54:55], v[82:83], v[108:109] op_sel_hi:[1,0,1]
	v_pk_fma_f32 v[54:55], v[98:99], v[54:55], v[92:93] op_sel_hi:[0,1,1]
	v_pk_fma_f32 v[52:53], v[98:99], v[52:53], v[88:89] op_sel_hi:[0,1,1]
	v_pk_fma_f32 v[54:55], v[10:11], v[62:63], v[54:55] op_sel_hi:[1,0,1]
	v_pk_fma_f32 v[52:53], v[8:9], v[62:63], v[52:53] op_sel_hi:[1,0,1]
	v_mul_f32_e32 v62, v129, v90
	v_pk_fma_f32 v[54:55], v[6:7], v[62:63], v[54:55] op_sel_hi:[1,0,1]
	v_pk_fma_f32 v[52:53], v[4:5], v[62:63], v[52:53] op_sel_hi:[1,0,1]
	v_or_b32_e32 v208, 0xc00, v96
	v_pk_fma_f32 v[54:55], v[2:3], v[94:95], v[54:55] op_sel_hi:[1,0,1]
	v_pk_fma_f32 v[52:53], v[0:1], v[94:95], v[52:53] op_sel_hi:[1,0,1]
	v_lshl_add_u64 v[88:89], v[100:101], 0, v[208:209]
	global_store_dwordx4 v[88:89], v[52:55], off nt
	v_mov_b32_e32 v62, v83
	v_or_b32_e32 v208, 0xe00, v96
	v_mov_b32_e32 v52, v71
	s_waitcnt vmcnt(14)
	v_pk_fma_f32 v[54:55], v[50:51], v[52:53], v[56:57] op_sel_hi:[1,0,1]
	v_mov_b32_e32 v56, v75
	v_pk_fma_f32 v[52:53], v[48:49], v[52:53], v[58:59] op_sel_hi:[1,0,1]
	v_pk_fma_f32 v[58:59], v[50:51], v[56:57], v[60:61] op_sel_hi:[1,0,1]
	v_mov_b32_e32 v60, v79
	v_pk_fma_f32 v[56:57], v[48:49], v[56:57], v[68:69] op_sel_hi:[1,0,1]
	v_pk_fma_f32 v[68:69], v[50:51], v[60:61], v[72:73] op_sel_hi:[1,0,1]
	v_pk_fma_f32 v[70:71], v[50:51], v[62:63], v[84:85] op_sel_hi:[1,0,1]
	v_pk_fma_f32 v[72:73], v[48:49], v[62:63], v[80:81] op_sel_hi:[1,0,1]
	v_mul_f32_e32 v62, v130, v87
	v_pk_fma_f32 v[60:61], v[48:49], v[60:61], v[76:77] op_sel_hi:[1,0,1]
	v_pk_mul_f32 v[74:75], v[12:13], v[62:63] op_sel_hi:[1,0]
	v_pk_mul_f32 v[76:77], v[14:15], v[62:63] op_sel_hi:[1,0]
	v_pk_fma_f32 v[48:49], v[98:99], v[48:49], v[74:75] op_sel_hi:[0,1,1]
	v_pk_fma_f32 v[50:51], v[98:99], v[50:51], v[76:77] op_sel_hi:[0,1,1]
	v_mul_f32_e32 v62, v128, v63
	v_pk_fma_f32 v[50:51], v[10:11], v[62:63], v[50:51] op_sel_hi:[1,0,1]
	v_pk_fma_f32 v[48:49], v[8:9], v[62:63], v[48:49] op_sel_hi:[1,0,1]
	v_mul_f32_e32 v62, v129, v91
	v_pk_fma_f32 v[50:51], v[6:7], v[62:63], v[50:51] op_sel_hi:[1,0,1]
	v_pk_fma_f32 v[48:49], v[4:5], v[62:63], v[48:49] op_sel_hi:[1,0,1]
	v_mov_b32_e32 v62, v95
	v_pk_fma_f32 v[50:51], v[2:3], v[62:63], v[50:51] op_sel_hi:[1,0,1]
	v_pk_fma_f32 v[48:49], v[0:1], v[62:63], v[48:49] op_sel_hi:[1,0,1]
	v_lshl_add_u64 v[62:63], v[100:101], 0, v[208:209]
	global_store_dwordx4 v[62:63], v[48:51], off nt
	s_waitcnt vmcnt(14)
	v_pk_fma_f32 v[80:81], v[46:47], v[64:65], v[54:55] op_sel_hi:[1,0,1]
	v_pk_fma_f32 v[82:83], v[44:45], v[64:65], v[52:53] op_sel_hi:[1,0,1]
	ds_read_b128 v[48:51], v131 offset:544
	ds_read_b128 v[52:55], v131 offset:1056
	ds_read_b128 v[76:79], v131 offset:3616
	v_or_b32_e32 v208, 0x1000, v96
	v_lshl_add_u64 v[102:103], v[100:101], 0, v[208:209]
	s_waitcnt lgkmcnt(2)
	v_pk_fma_f32 v[84:85], v[46:47], v[48:49], v[58:59] op_sel_hi:[1,0,1]
	v_pk_fma_f32 v[86:87], v[44:45], v[48:49], v[56:57] op_sel_hi:[1,0,1]
	s_waitcnt lgkmcnt(1)
	v_pk_fma_f32 v[90:91], v[44:45], v[52:53], v[60:61] op_sel_hi:[1,0,1]
	ds_read_b128 v[56:59], v131 offset:1568
	ds_read_b128 v[60:63], v131 offset:2080
	v_pk_fma_f32 v[88:89], v[46:47], v[52:53], v[68:69] op_sel_hi:[1,0,1]
	v_or_b32_e32 v208, 0x1200, v96
	global_store_dwordx4 v[118:119], v[132:135], off nt
	s_waitcnt lgkmcnt(1)
	v_pk_fma_f32 v[92:93], v[46:47], v[56:57], v[70:71] op_sel_hi:[1,0,1]
	s_waitcnt lgkmcnt(0)
	v_mul_f32_e32 v60, v130, v60
	v_pk_mul_f32 v[68:69], v[14:15], v[60:61] op_sel_hi:[1,0]
	v_pk_mul_f32 v[70:71], v[12:13], v[60:61] op_sel_hi:[1,0]
	v_pk_fma_f32 v[94:95], v[44:45], v[56:57], v[72:73] op_sel_hi:[1,0,1]
	v_pk_fma_f32 v[44:45], v[98:99], v[44:45], v[70:71] op_sel_hi:[0,1,1]
	v_pk_fma_f32 v[46:47], v[98:99], v[46:47], v[68:69] op_sel_hi:[0,1,1]
	ds_read_b128 v[68:71], v131 offset:2592
	ds_read_b128 v[72:75], v131 offset:3104
	s_waitcnt lgkmcnt(1)
	v_mul_f32_e32 v60, v128, v68
	v_pk_fma_f32 v[44:45], v[8:9], v[60:61], v[44:45] op_sel_hi:[1,0,1]
	v_pk_fma_f32 v[46:47], v[10:11], v[60:61], v[46:47] op_sel_hi:[1,0,1]
	s_waitcnt lgkmcnt(0)
	v_mul_f32_e32 v60, v129, v72
	v_pk_fma_f32 v[44:45], v[4:5], v[60:61], v[44:45] op_sel_hi:[1,0,1]
	v_pk_fma_f32 v[46:47], v[6:7], v[60:61], v[46:47] op_sel_hi:[1,0,1]
	v_pk_fma_f32 v[44:45], v[0:1], v[76:77], v[44:45] op_sel_hi:[1,0,1]
	v_pk_fma_f32 v[46:47], v[2:3], v[76:77], v[46:47] op_sel_hi:[1,0,1]
	v_mul_f32_e32 v60, v130, v61
	global_store_dwordx4 v[102:103], v[44:47], off nt
	s_waitcnt vmcnt(15)
	s_nop 0
	v_pk_fma_f32 v[44:45], v[42:43], v[64:65], v[80:81] op_sel:[0,1,0]
	v_pk_fma_f32 v[46:47], v[40:41], v[64:65], v[82:83] op_sel:[0,1,0]
	v_pk_fma_f32 v[64:65], v[42:43], v[48:49], v[84:85] op_sel:[0,1,0]
	v_pk_mul_f32 v[84:85], v[14:15], v[60:61] op_sel_hi:[1,0]
	v_pk_mul_f32 v[60:61], v[12:13], v[60:61] op_sel_hi:[1,0]
	v_pk_fma_f32 v[48:49], v[40:41], v[48:49], v[86:87] op_sel:[0,1,0]
	v_pk_fma_f32 v[80:81], v[42:43], v[52:53], v[88:89] op_sel:[0,1,0]
	v_pk_fma_f32 v[52:53], v[40:41], v[52:53], v[90:91] op_sel:[0,1,0]
	v_pk_fma_f32 v[82:83], v[42:43], v[56:57], v[92:93] op_sel:[0,1,0]
	v_pk_fma_f32 v[56:57], v[40:41], v[56:57], v[94:95] op_sel:[0,1,0]
	v_pk_fma_f32 v[40:41], v[98:99], v[40:41], v[60:61] op_sel_hi:[0,1,1]
	v_pk_fma_f32 v[42:43], v[98:99], v[42:43], v[84:85] op_sel_hi:[0,1,1]
	v_mul_f32_e32 v60, v128, v69
	v_pk_fma_f32 v[40:41], v[8:9], v[60:61], v[40:41] op_sel_hi:[1,0,1]
	v_pk_fma_f32 v[42:43], v[10:11], v[60:61], v[42:43] op_sel_hi:[1,0,1]
	v_mul_f32_e32 v60, v129, v73
	v_pk_fma_f32 v[40:41], v[4:5], v[60:61], v[40:41] op_sel_hi:[1,0,1]
	v_pk_fma_f32 v[42:43], v[6:7], v[60:61], v[42:43] op_sel_hi:[1,0,1]
	v_pk_fma_f32 v[40:41], v[0:1], v[76:77], v[40:41] op_sel:[0,1,0]
	v_pk_fma_f32 v[42:43], v[2:3], v[76:77], v[42:43] op_sel:[0,1,0]
	v_lshl_add_u64 v[60:61], v[100:101], 0, v[208:209]
	global_store_dwordx4 v[60:61], v[40:43], off nt
	s_waitcnt vmcnt(15)
	v_pk_fma_f32 v[52:53], v[36:37], v[54:55], v[52:53] op_sel_hi:[1,0,1]
	v_pk_fma_f32 v[60:61], v[38:39], v[58:59], v[82:83] op_sel_hi:[1,0,1]
	v_pk_fma_f32 v[40:41], v[38:39], v[66:67], v[44:45] op_sel_hi:[1,0,1]
	v_pk_fma_f32 v[42:43], v[36:37], v[66:67], v[46:47] op_sel_hi:[1,0,1]
	v_pk_fma_f32 v[44:45], v[38:39], v[50:51], v[64:65] op_sel_hi:[1,0,1]
	v_pk_fma_f32 v[46:47], v[36:37], v[50:51], v[48:49] op_sel_hi:[1,0,1]
	v_mul_f32_e32 v50, v130, v62
	v_pk_mul_f32 v[64:65], v[14:15], v[50:51] op_sel_hi:[1,0]
	v_pk_mul_f32 v[68:69], v[12:13], v[50:51] op_sel_hi:[1,0]
	v_pk_fma_f32 v[48:49], v[38:39], v[54:55], v[80:81] op_sel_hi:[1,0,1]
	v_pk_fma_f32 v[56:57], v[36:37], v[58:59], v[56:57] op_sel_hi:[1,0,1]
	v_pk_fma_f32 v[36:37], v[98:99], v[36:37], v[68:69] op_sel_hi:[0,1,1]
	v_pk_fma_f32 v[38:39], v[98:99], v[38:39], v[64:65] op_sel_hi:[0,1,1]
	v_mul_f32_e32 v50, v128, v70
	v_pk_fma_f32 v[36:37], v[8:9], v[50:51], v[36:37] op_sel_hi:[1,0,1]
	v_pk_fma_f32 v[38:39], v[10:11], v[50:51], v[38:39] op_sel_hi:[1,0,1]
	v_mul_f32_e32 v50, v129, v74
	v_pk_fma_f32 v[36:37], v[4:5], v[50:51], v[36:37] op_sel_hi:[1,0,1]
	v_pk_fma_f32 v[38:39], v[6:7], v[50:51], v[38:39] op_sel_hi:[1,0,1]
	v_or_b32_e32 v208, 0x1400, v96
	v_pk_fma_f32 v[36:37], v[0:1], v[78:79], v[36:37] op_sel_hi:[1,0,1]
	v_pk_fma_f32 v[38:39], v[2:3], v[78:79], v[38:39] op_sel_hi:[1,0,1]
	v_lshl_add_u64 v[64:65], v[100:101], 0, v[208:209]
	global_store_dwordx4 v[64:65], v[36:39], off nt
	v_mov_b32_e32 v50, v59
	v_or_b32_e32 v208, 0x1600, v96
	v_mov_b32_e32 v38, v67
	s_waitcnt vmcnt(15)
	v_pk_fma_f32 v[36:37], v[34:35], v[38:39], v[40:41] op_sel_hi:[1,0,1]
	v_pk_fma_f32 v[38:39], v[32:33], v[38:39], v[42:43] op_sel_hi:[1,0,1]
	v_mov_b32_e32 v42, v51
	v_pk_fma_f32 v[40:41], v[34:35], v[42:43], v[44:45] op_sel_hi:[1,0,1]
	v_pk_fma_f32 v[42:43], v[32:33], v[42:43], v[46:47] op_sel_hi:[1,0,1]
	v_mov_b32_e32 v46, v55
	v_pk_fma_f32 v[44:45], v[34:35], v[46:47], v[48:49] op_sel_hi:[1,0,1]
	v_pk_fma_f32 v[46:47], v[32:33], v[46:47], v[52:53] op_sel_hi:[1,0,1]
	v_mul_f32_e32 v52, v130, v63
	v_pk_mul_f32 v[54:55], v[14:15], v[52:53] op_sel_hi:[1,0]
	v_pk_mul_f32 v[52:53], v[12:13], v[52:53] op_sel_hi:[1,0]
	v_pk_fma_f32 v[48:49], v[34:35], v[50:51], v[60:61] op_sel_hi:[1,0,1]
	v_pk_fma_f32 v[50:51], v[32:33], v[50:51], v[56:57] op_sel_hi:[1,0,1]
	v_pk_fma_f32 v[32:33], v[98:99], v[32:33], v[52:53] op_sel_hi:[0,1,1]
	v_pk_fma_f32 v[34:35], v[98:99], v[34:35], v[54:55] op_sel_hi:[0,1,1]
	v_mul_f32_e32 v52, v128, v71
	v_pk_fma_f32 v[32:33], v[8:9], v[52:53], v[32:33] op_sel_hi:[1,0,1]
	v_pk_fma_f32 v[34:35], v[10:11], v[52:53], v[34:35] op_sel_hi:[1,0,1]
	v_mul_f32_e32 v52, v129, v75
	v_pk_fma_f32 v[32:33], v[4:5], v[52:53], v[32:33] op_sel_hi:[1,0,1]
	v_pk_fma_f32 v[34:35], v[6:7], v[52:53], v[34:35] op_sel_hi:[1,0,1]
	v_mov_b32_e32 v52, v79
	v_pk_fma_f32 v[32:33], v[0:1], v[52:53], v[32:33] op_sel_hi:[1,0,1]
	v_pk_fma_f32 v[34:35], v[2:3], v[52:53], v[34:35] op_sel_hi:[1,0,1]
	v_lshl_add_u64 v[52:53], v[100:101], 0, v[208:209]
	global_store_dwordx4 v[52:53], v[32:35], off nt
	ds_read_b128 v[32:35], v131 offset:48
	v_or_b32_e32 v208, 0x1800, v96
	v_lshl_add_u64 v[80:81], v[100:101], 0, v[208:209]
	v_or_b32_e32 v208, 0x1a00, v96
	s_waitcnt vmcnt(15) lgkmcnt(0)
	v_pk_fma_f32 v[60:61], v[30:31], v[32:33], v[36:37] op_sel_hi:[1,0,1]
	v_pk_fma_f32 v[62:63], v[28:29], v[32:33], v[38:39] op_sel_hi:[1,0,1]
	ds_read_b128 v[36:39], v131 offset:560
	s_waitcnt vmcnt(14)
	v_pk_fma_f32 v[60:61], v[26:27], v[32:33], v[60:61] op_sel:[0,1,0]
	v_pk_fma_f32 v[32:33], v[24:25], v[32:33], v[62:63] op_sel:[0,1,0]
	s_waitcnt lgkmcnt(0)
	v_pk_fma_f32 v[64:65], v[30:31], v[36:37], v[40:41] op_sel_hi:[1,0,1]
	v_pk_fma_f32 v[66:67], v[28:29], v[36:37], v[42:43] op_sel_hi:[1,0,1]
	ds_read_b128 v[40:43], v131 offset:1072
	v_pk_fma_f32 v[62:63], v[26:27], v[36:37], v[64:65] op_sel:[0,1,0]
	v_pk_fma_f32 v[36:37], v[24:25], v[36:37], v[66:67] op_sel:[0,1,0]
	s_waitcnt lgkmcnt(0)
	v_pk_fma_f32 v[68:69], v[30:31], v[40:41], v[44:45] op_sel_hi:[1,0,1]
	v_pk_fma_f32 v[70:71], v[28:29], v[40:41], v[46:47] op_sel_hi:[1,0,1]
	ds_read_b128 v[44:47], v131 offset:1584
	v_pk_fma_f32 v[64:65], v[26:27], v[40:41], v[68:69] op_sel:[0,1,0]
	v_pk_fma_f32 v[40:41], v[24:25], v[40:41], v[70:71] op_sel:[0,1,0]
	s_waitcnt lgkmcnt(0)
	v_pk_fma_f32 v[72:73], v[30:31], v[44:45], v[48:49] op_sel_hi:[1,0,1]
	v_pk_fma_f32 v[74:75], v[28:29], v[44:45], v[50:51] op_sel_hi:[1,0,1]
	ds_read_b128 v[48:51], v131 offset:2096
	v_pk_fma_f32 v[66:67], v[26:27], v[44:45], v[72:73] op_sel:[0,1,0]
	v_pk_fma_f32 v[44:45], v[24:25], v[44:45], v[74:75] op_sel:[0,1,0]
	s_waitcnt vmcnt(13)
	v_pk_fma_f32 v[40:41], v[20:21], v[42:43], v[40:41] op_sel_hi:[1,0,1]
	v_pk_fma_f32 v[44:45], v[20:21], v[46:47], v[44:45] op_sel_hi:[1,0,1]
	s_waitcnt lgkmcnt(0)
	v_mul_f32_e32 v48, v130, v48
	v_pk_mul_f32 v[52:53], v[14:15], v[48:49] op_sel_hi:[1,0]
	v_pk_mul_f32 v[54:55], v[12:13], v[48:49] op_sel_hi:[1,0]
	v_pk_fma_f32 v[52:53], v[98:99], v[30:31], v[52:53] op_sel_hi:[0,1,1]
	v_pk_fma_f32 v[54:55], v[98:99], v[28:29], v[54:55] op_sel_hi:[0,1,1]
	ds_read_b128 v[28:31], v131 offset:2608
	s_waitcnt lgkmcnt(0)
	v_mul_f32_e32 v28, v128, v28
	v_pk_fma_f32 v[56:57], v[8:9], v[28:29], v[54:55] op_sel_hi:[1,0,1]
	v_pk_fma_f32 v[58:59], v[10:11], v[28:29], v[52:53] op_sel_hi:[1,0,1]
	ds_read_b128 v[52:55], v131 offset:3120
	v_mul_f32_e32 v30, v128, v30
	s_waitcnt lgkmcnt(0)
	v_mul_f32_e32 v28, v129, v52
	v_pk_fma_f32 v[76:77], v[4:5], v[28:29], v[56:57] op_sel_hi:[1,0,1]
	v_pk_fma_f32 v[78:79], v[6:7], v[28:29], v[58:59] op_sel_hi:[1,0,1]
	ds_read_b128 v[56:59], v131 offset:3632
	v_mul_f32_e32 v28, v130, v49
	v_pk_mul_f32 v[48:49], v[14:15], v[28:29] op_sel_hi:[1,0]
	v_pk_mul_f32 v[68:69], v[12:13], v[28:29] op_sel_hi:[1,0]
	v_pk_fma_f32 v[26:27], v[98:99], v[26:27], v[48:49] op_sel_hi:[0,1,1]
	v_pk_fma_f32 v[24:25], v[98:99], v[24:25], v[68:69] op_sel_hi:[0,1,1]
	v_mul_f32_e32 v28, v128, v29
	v_pk_fma_f32 v[24:25], v[8:9], v[28:29], v[24:25] op_sel_hi:[1,0,1]
	v_pk_fma_f32 v[26:27], v[10:11], v[28:29], v[26:27] op_sel_hi:[1,0,1]
	v_mul_f32_e32 v28, v129, v53
	v_pk_fma_f32 v[24:25], v[4:5], v[28:29], v[24:25] op_sel_hi:[1,0,1]
	v_pk_fma_f32 v[26:27], v[6:7], v[28:29], v[26:27] op_sel_hi:[1,0,1]
	s_waitcnt lgkmcnt(0)
	v_pk_fma_f32 v[24:25], v[0:1], v[56:57], v[24:25] op_sel:[0,1,0]
	v_pk_fma_f32 v[26:27], v[2:3], v[56:57], v[26:27] op_sel:[0,1,0]
	v_lshl_add_u64 v[28:29], v[100:101], 0, v[208:209]
	global_store_dwordx4 v[28:29], v[24:27], off nt
	v_pk_fma_f32 v[76:77], v[0:1], v[56:57], v[76:77] op_sel_hi:[1,0,1]
	v_pk_fma_f32 v[78:79], v[2:3], v[56:57], v[78:79] op_sel_hi:[1,0,1]
	v_pk_fma_f32 v[24:25], v[22:23], v[34:35], v[60:61] op_sel_hi:[1,0,1]
	v_pk_fma_f32 v[26:27], v[20:21], v[34:35], v[32:33] op_sel_hi:[1,0,1]
	v_mul_f32_e32 v34, v130, v50
	v_pk_mul_f32 v[52:53], v[14:15], v[34:35] op_sel_hi:[1,0]
	v_pk_mul_f32 v[56:57], v[12:13], v[34:35] op_sel_hi:[1,0]
	v_pk_fma_f32 v[28:29], v[22:23], v[38:39], v[62:63] op_sel_hi:[1,0,1]
	v_pk_fma_f32 v[32:33], v[20:21], v[38:39], v[36:37] op_sel_hi:[1,0,1]
	v_pk_fma_f32 v[36:37], v[22:23], v[42:43], v[64:65] op_sel_hi:[1,0,1]
	v_pk_fma_f32 v[48:49], v[22:23], v[46:47], v[66:67] op_sel_hi:[1,0,1]
	v_pk_fma_f32 v[20:21], v[98:99], v[20:21], v[56:57] op_sel_hi:[0,1,1]
	v_pk_fma_f32 v[22:23], v[98:99], v[22:23], v[52:53] op_sel_hi:[0,1,1]
	v_pk_fma_f32 v[20:21], v[8:9], v[30:31], v[20:21] op_sel_hi:[1,0,1]
	v_pk_fma_f32 v[22:23], v[10:11], v[30:31], v[22:23] op_sel_hi:[1,0,1]
	v_mul_f32_e32 v30, v129, v54
	v_pk_fma_f32 v[20:21], v[4:5], v[30:31], v[20:21] op_sel_hi:[1,0,1]
	v_pk_fma_f32 v[22:23], v[6:7], v[30:31], v[22:23] op_sel_hi:[1,0,1]
	v_or_b32_e32 v208, 0x1c00, v96
	v_pk_fma_f32 v[20:21], v[0:1], v[58:59], v[20:21] op_sel_hi:[1,0,1]
	v_pk_fma_f32 v[22:23], v[2:3], v[58:59], v[22:23] op_sel_hi:[1,0,1]
	v_lshl_add_u64 v[52:53], v[100:101], 0, v[208:209]
	global_store_dwordx4 v[52:53], v[20:23], off nt
	v_or_b32_e32 v208, 0x1e00, v96
	global_store_dwordx4 v[80:81], v[76:79], off nt
	v_mov_b32_e32 v20, v35
	s_waitcnt vmcnt(15)
	v_pk_fma_f32 v[22:23], v[18:19], v[20:21], v[24:25] op_sel_hi:[1,0,1]
	v_mov_b32_e32 v24, v39
	v_pk_fma_f32 v[20:21], v[16:17], v[20:21], v[26:27] op_sel_hi:[1,0,1]
	v_pk_fma_f32 v[26:27], v[18:19], v[24:25], v[28:29] op_sel_hi:[1,0,1]
	v_mov_b32_e32 v28, v43
	v_pk_fma_f32 v[24:25], v[16:17], v[24:25], v[32:33] op_sel_hi:[1,0,1]
	v_pk_fma_f32 v[34:35], v[18:19], v[28:29], v[36:37] op_sel_hi:[1,0,1]
	v_pk_fma_f32 v[32:33], v[16:17], v[28:29], v[40:41] op_sel_hi:[1,0,1]
	v_mov_b32_e32 v28, v47
	v_pk_fma_f32 v[38:39], v[18:19], v[28:29], v[48:49] op_sel_hi:[1,0,1]
	v_pk_fma_f32 v[36:37], v[16:17], v[28:29], v[44:45] op_sel_hi:[1,0,1]
	v_mul_f32_e32 v28, v130, v51
	v_pk_mul_f32 v[14:15], v[14:15], v[28:29] op_sel_hi:[1,0]
	v_pk_mul_f32 v[12:13], v[12:13], v[28:29] op_sel_hi:[1,0]
	v_pk_fma_f32 v[14:15], v[98:99], v[18:19], v[14:15] op_sel_hi:[0,1,1]
	v_pk_fma_f32 v[12:13], v[98:99], v[16:17], v[12:13] op_sel_hi:[0,1,1]
	v_mul_f32_e32 v16, v128, v31
	v_pk_fma_f32 v[8:9], v[8:9], v[16:17], v[12:13] op_sel_hi:[1,0,1]
	v_pk_fma_f32 v[10:11], v[10:11], v[16:17], v[14:15] op_sel_hi:[1,0,1]
	v_mul_f32_e32 v12, v129, v55
	v_pk_fma_f32 v[4:5], v[4:5], v[12:13], v[8:9] op_sel_hi:[1,0,1]
	v_pk_fma_f32 v[6:7], v[6:7], v[12:13], v[10:11] op_sel_hi:[1,0,1]
	v_mov_b32_e32 v8, v59
	v_pk_fma_f32 v[0:1], v[0:1], v[8:9], v[4:5] op_sel_hi:[1,0,1]
	v_pk_fma_f32 v[2:3], v[2:3], v[8:9], v[6:7] op_sel_hi:[1,0,1]
	v_lshl_add_u64 v[4:5], v[100:101], 0, v[208:209]
	global_store_dwordx4 v[4:5], v[0:3], off nt
	v_and_b32_e32 v14, 64, v230
	v_add_u32_e32 v14, 64, v14
	v_cvt_f32_ubyte0_e32 v1, s20
	v_mul_f32_e32 v2, v124, v1
	v_cmp_gt_f32_e32 vcc, s3, v2
	v_lshl_add_u32 v0, v126, 11, v127
	ds_write_b128 v0, v[20:23] offset:8192
	ds_write_b128 v0, v[24:27] offset:8704
	ds_write_b128 v0, v[32:35] offset:9216
	ds_write_b128 v0, v[36:39] offset:9728
	v_cndmask_b32_e32 v2, 0, v233, vcc
	v_fmac_f32_e32 v2, v124, v1
	v_exp_f32_e32 v1, v2
	v_lshlrev_b32_e32 v0, 2, v125
	s_and_b64 s[20:21], vcc, exec
	v_add_u32_e32 v15, s31, v0
	s_cselect_b32 s20, 0xffffffc0, 0
	s_add_i32 s31, s31, s34
	v_add_u32_e32 v4, s31, v0
	s_waitcnt lgkmcnt(0)
	s_barrier
	v_ldexp_f32 v2, v1, s20
	ds_read2st64_b32 v[0:1], v4 offset0:32 offset1:33
	ds_read2st64_b32 v[12:13], v4 offset0:40 offset1:41
	ds_read2st64_b32 v[16:17], v4 offset0:48 offset1:49
	ds_read2st64_b32 v[18:19], v4 offset0:56 offset1:57
	ds_read2st64_b32 v[10:11], v4 offset0:64 offset1:65
	ds_read2st64_b32 v[8:9], v4 offset0:72 offset1:73
	ds_read2st64_b32 v[6:7], v4 offset0:80 offset1:81
	ds_read2st64_b32 v[4:5], v4 offset0:88 offset1:89
	s_waitcnt lgkmcnt(7)
	v_pk_add_f32 v[0:1], v[0:1], 0 op_sel_hi:[1,0]
	v_add_u32_e32 v3, s34, v15
	s_waitcnt lgkmcnt(6)
	v_pk_add_f32 v[0:1], v[0:1], v[12:13]
	s_waitcnt lgkmcnt(5)
	v_pk_add_f32 v[0:1], v[0:1], v[16:17]
	s_waitcnt lgkmcnt(4)
	v_pk_add_f32 v[12:13], v[0:1], v[18:19]
	ds_read2st64_b32 v[0:1], v3 offset1:1
	ds_read2st64_b32 v[16:17], v15 offset0:8 offset1:9
	s_waitcnt lgkmcnt(5)
	v_pk_add_f32 v[10:11], v[12:13], v[10:11]
	s_waitcnt lgkmcnt(0)
	v_pk_mul_f32 v[16:17], v[0:1], v[16:17]
	s_nop 0
	v_add_f32_e32 v3, v16, v17
	v_xor_b32_e32 v16, 1, v230
	v_cmp_lt_i32_e32 vcc, v16, v14
	v_pk_add_f32 v[8:9], v[10:11], v[8:9]
	s_nop 0
	v_cndmask_b32_e32 v16, v230, v16, vcc
	v_lshlrev_b32_e32 v16, 2, v16
	ds_bpermute_b32 v17, v16, v3
	v_pk_add_f32 v[6:7], v[8:9], v[6:7]
	s_waitcnt lgkmcnt(0)
	v_add_f32_e32 v3, v3, v17
	v_xor_b32_e32 v17, 2, v230
	v_cmp_lt_i32_e32 vcc, v17, v14
	v_pk_add_f32 v[4:5], v[6:7], v[4:5]
	s_nop 0
	v_cndmask_b32_e32 v17, v230, v17, vcc
	v_lshlrev_b32_e32 v17, 2, v17
	ds_bpermute_b32 v18, v17, v3
	s_waitcnt lgkmcnt(0)
	v_add_f32_e32 v3, v3, v18
	v_xor_b32_e32 v18, 4, v230
	v_cmp_lt_i32_e32 vcc, v18, v14
	s_nop 1
	v_cndmask_b32_e32 v18, v230, v18, vcc
	v_lshlrev_b32_e32 v18, 2, v18
	ds_bpermute_b32 v19, v18, v3
	s_waitcnt lgkmcnt(0)
	v_add_f32_e32 v3, v3, v19
	v_xor_b32_e32 v19, 8, v230
	v_cmp_lt_i32_e32 vcc, v19, v14
	s_nop 1
	v_cndmask_b32_e32 v19, v230, v19, vcc
	v_lshlrev_b32_e32 v19, 2, v19
	ds_bpermute_b32 v20, v19, v3
	s_waitcnt lgkmcnt(0)
	v_add_f32_e32 v3, v3, v20
	v_xor_b32_e32 v20, 16, v230
	v_cmp_lt_i32_e32 vcc, v20, v14
	s_nop 1
	v_cndmask_b32_e32 v20, v230, v20, vcc
	v_lshlrev_b32_e32 v20, 2, v20
	ds_bpermute_b32 v21, v20, v3
	s_waitcnt lgkmcnt(0)
	v_add_f32_e32 v3, v3, v21
	v_xor_b32_e32 v21, 32, v230
	v_cmp_lt_i32_e32 vcc, v21, v14
	s_nop 1
	v_cndmask_b32_e32 v14, v230, v21, vcc
	v_lshlrev_b32_e32 v21, 2, v14
	ds_bpermute_b32 v14, v21, v3
	s_waitcnt lgkmcnt(0)
	v_add_f32_e32 v3, v3, v14
	v_cvt_f32_ubyte0_e32 v14, s23
	v_mul_f32_e32 v22, v124, v14
	v_cmp_gt_f32_e32 vcc, s3, v22
	s_and_b64 s[20:21], vcc, exec
	s_cselect_b32 s20, 0xffffffc0, 0
	v_cndmask_b32_e32 v22, 0, v233, vcc
	v_fmac_f32_e32 v22, v124, v14
	v_exp_f32_e32 v14, v22
	ds_read2st64_b32 v[22:23], v15 offset0:16 offset1:17
	s_cmp_eq_u32 s23, 0
	v_ldexp_f32 v14, v14, s20
	v_mul_f32_e32 v14, v14, v3
	s_waitcnt lgkmcnt(0)
	v_pk_mul_f32 v[6:7], v[22:23], v[14:15] op_sel_hi:[1,0]
	s_nop 0
	v_pk_fma_f32 v[2:3], v[2:3], v[4:5], v[6:7] op_sel_hi:[0,1,1]
	s_cbranch_scc1 .LBB0_449
	ds_read2st64_b32 v[4:5], v15 offset0:10 offset1:11
	s_add_i32 s20, s23, -1
	s_waitcnt lgkmcnt(0)
	v_pk_mul_f32 v[4:5], v[0:1], v[4:5]
	s_nop 0
	v_add_f32_e32 v4, v4, v5
	ds_bpermute_b32 v5, v16, v4
	s_waitcnt lgkmcnt(0)
	v_add_f32_e32 v4, v4, v5
	ds_bpermute_b32 v5, v17, v4
	s_waitcnt lgkmcnt(0)
	v_add_f32_e32 v4, v4, v5
	ds_bpermute_b32 v5, v18, v4
	s_waitcnt lgkmcnt(0)
	v_add_f32_e32 v4, v4, v5
	ds_bpermute_b32 v5, v19, v4
	s_waitcnt lgkmcnt(0)
	v_add_f32_e32 v4, v4, v5
	ds_bpermute_b32 v5, v20, v4
	s_waitcnt lgkmcnt(0)
	v_add_f32_e32 v4, v4, v5
	ds_bpermute_b32 v5, v21, v4
	s_waitcnt lgkmcnt(0)
	v_add_f32_e32 v4, v4, v5
	v_cvt_f32_u32_e32 v5, s20
	v_mul_f32_e32 v6, v124, v5
	v_cmp_gt_f32_e32 vcc, s3, v6
	s_and_b64 s[20:21], vcc, exec
	s_cselect_b32 s20, 0xffffffc0, 0
	v_cndmask_b32_e32 v6, 0, v233, vcc
	v_fmac_f32_e32 v6, v124, v5
	v_exp_f32_e32 v5, v6
	ds_read2st64_b32 v[6:7], v15 offset0:18 offset1:19
	v_ldexp_f32 v5, v5, s20
	v_mul_f32_e32 v4, v5, v4
	s_waitcnt lgkmcnt(0)
	v_pk_fma_f32 v[2:3], v[6:7], v[4:5], v[2:3] op_sel_hi:[1,0,1]
